# v9 plus: s5_load_coef 64 serialized coefficient loads batched behind one wait (pb+4 and pb+6), S5 carry scan spread to one wave per workgroup over 64 workgroups
# speedup vs baseline: 1.0568x; 1.0122x over previous
.LBB0_697:
	s_cmpk_gt_u32 s10, 0x101f
	s_cbranch_scc1 .LBB0_962
	v_ashrrev_i32_e32 v28, 6, v60
	v_add_u32_e32 v60, 0xffffbf80, v28
	v_lshl_add_u32 v29, s10, 3, v60
	v_readlane_b32 s2, v255, 24
	v_mov_b32_e32 v0, 0x48000
	v_and_b32_e32 v61, 31, v29
	v_mov_b32_e32 v6, v160
	v_mad_i64_i32 v[0:1], s[2:3], s2, v0, v[2:3]
	s_mov_b64 s[2:3], 0x1ec32000
	v_and_b32_e32 v7, 63, v6
	v_lshlrev_b32_e32 v4, 9, v61
	v_lshl_add_u64 v[50:51], v[0:1], 0, s[2:3]
	v_lshl_or_b32 v162, v7, 3, v4
	v_lshl_add_u64 v[4:5], v[50:51], 0, v[162:163]
	global_load_dwordx2 v[54:55], v[4:5], off
	s_mov_b64 s[2:3], 0x1ec3a000
	v_lshl_add_u64 v[52:53], v[0:1], 0, s[2:3]
	v_lshlrev_b32_e32 v0, 11, v61
	v_lshlrev_b32_e32 v1, 6, v6
	s_movk_i32 s2, 0x400
	v_and_or_b32 v4, v1, s2, v0
	v_lshlrev_b32_e32 v0, 1, v6
	v_and_b32_e32 v5, 30, v0
	v_or_b32_e32 v0, v4, v5
	v_lshlrev_b32_e32 v162, 2, v0
	v_cmp_gt_u32_e32 vcc, 32, v7
	v_lshl_add_u64 v[0:1], v[52:53], 0, v[162:163]
	v_mov_b32_e32 v20, 0
	v_mov_b32_e32 v24, 0
	s_and_saveexec_b64 s[2:3], vcc
	s_cbranch_execz .LBB0_700
	global_load_dword v164, v[0:1], off
.LBB0_700:
	s_or_b64 exec, exec, s[2:3]
	s_and_saveexec_b64 s[2:3], vcc
	s_cbranch_execz .LBB0_702
	global_load_dword v165, v[0:1], off offset:4
.LBB0_702:
	s_or_b64 exec, exec, s[2:3]
	v_or_b32_e32 v6, 0x80, v4
	v_or_b32_e32 v0, v6, v5
	v_lshlrev_b32_e32 v162, 2, v0
	v_lshl_add_u64 v[0:1], v[52:53], 0, v[162:163]
	v_mov_b32_e32 v25, 0
	v_mov_b32_e32 v30, 0
	s_and_saveexec_b64 s[2:3], vcc
	s_cbranch_execz .LBB0_704
	global_load_dword v166, v[0:1], off
.LBB0_704:
	s_or_b64 exec, exec, s[2:3]
	s_and_saveexec_b64 s[2:3], vcc
	s_cbranch_execz .LBB0_706
	global_load_dword v167, v[0:1], off offset:4
.LBB0_706:
	s_or_b64 exec, exec, s[2:3]
	v_or_b32_e32 v7, 0x100, v4
	v_or_b32_e32 v0, v7, v5
	v_lshlrev_b32_e32 v162, 2, v0
	v_lshl_add_u64 v[0:1], v[52:53], 0, v[162:163]
	v_mov_b32_e32 v21, 0
	v_mov_b32_e32 v31, 0
	s_and_saveexec_b64 s[2:3], vcc
	s_cbranch_execz .LBB0_708
	global_load_dword v170, v[0:1], off
.LBB0_708:
	s_or_b64 exec, exec, s[2:3]
	s_and_saveexec_b64 s[2:3], vcc
	s_cbranch_execz .LBB0_710
	global_load_dword v171, v[0:1], off offset:4
.LBB0_710:
	s_or_b64 exec, exec, s[2:3]
	v_or_b32_e32 v8, 0x180, v4
	v_or_b32_e32 v0, v8, v5
	v_lshlrev_b32_e32 v162, 2, v0
	v_lshl_add_u64 v[0:1], v[52:53], 0, v[162:163]
	v_mov_b32_e32 v26, 0
	v_mov_b32_e32 v32, 0
	s_and_saveexec_b64 s[2:3], vcc
	s_cbranch_execz .LBB0_712
	global_load_dword v172, v[0:1], off
.LBB0_712:
	s_or_b64 exec, exec, s[2:3]
	s_and_saveexec_b64 s[2:3], vcc
	s_cbranch_execz .LBB0_714
	global_load_dword v173, v[0:1], off offset:4
.LBB0_714:
	s_or_b64 exec, exec, s[2:3]
	v_or_b32_e32 v9, 0x200, v4
	v_or_b32_e32 v0, v9, v5
	v_lshlrev_b32_e32 v162, 2, v0
	v_lshl_add_u64 v[0:1], v[52:53], 0, v[162:163]
	v_mov_b32_e32 v22, 0
	v_mov_b32_e32 v33, 0
	s_and_saveexec_b64 s[2:3], vcc
	s_cbranch_execz .LBB0_716
	global_load_dword v174, v[0:1], off
.LBB0_716:
	s_or_b64 exec, exec, s[2:3]
	s_and_saveexec_b64 s[2:3], vcc
	s_cbranch_execz .LBB0_718
	global_load_dword v175, v[0:1], off offset:4
.LBB0_718:
	s_or_b64 exec, exec, s[2:3]
	v_or_b32_e32 v10, 0x280, v4
	v_or_b32_e32 v0, v10, v5
	v_lshlrev_b32_e32 v162, 2, v0
	v_lshl_add_u64 v[0:1], v[52:53], 0, v[162:163]
	v_mov_b32_e32 v27, 0
	v_mov_b32_e32 v34, 0
	s_and_saveexec_b64 s[2:3], vcc
	s_cbranch_execz .LBB0_720
	global_load_dword v176, v[0:1], off
.LBB0_720:
	s_or_b64 exec, exec, s[2:3]
	s_and_saveexec_b64 s[2:3], vcc
	s_cbranch_execz .LBB0_722
	global_load_dword v177, v[0:1], off offset:4
.LBB0_722:
	s_or_b64 exec, exec, s[2:3]
	v_or_b32_e32 v11, 0x300, v4
	v_or_b32_e32 v0, v11, v5
	v_lshlrev_b32_e32 v162, 2, v0
	v_lshl_add_u64 v[0:1], v[52:53], 0, v[162:163]
	v_mov_b32_e32 v23, 0
	v_mov_b32_e32 v35, 0
	s_and_saveexec_b64 s[2:3], vcc
	s_cbranch_execz .LBB0_724
	global_load_dword v178, v[0:1], off
.LBB0_724:
	s_or_b64 exec, exec, s[2:3]
	s_and_saveexec_b64 s[2:3], vcc
	s_cbranch_execz .LBB0_726
	global_load_dword v179, v[0:1], off offset:4
.LBB0_726:
	s_or_b64 exec, exec, s[2:3]
	v_or_b32_e32 v13, 0x380, v4
	v_or_b32_e32 v0, v13, v5
	v_lshlrev_b32_e32 v162, 2, v0
	v_lshl_add_u64 v[0:1], v[52:53], 0, v[162:163]
	v_mov_b32_e32 v37, 0
	v_mov_b32_e32 v36, 0
	s_and_saveexec_b64 s[2:3], vcc
	s_cbranch_execz .LBB0_728
	global_load_dword v180, v[0:1], off
.LBB0_728:
	s_or_b64 exec, exec, s[2:3]
	s_and_saveexec_b64 s[2:3], vcc
	s_cbranch_execz .LBB0_730
	global_load_dword v181, v[0:1], off offset:4
.LBB0_730:
	s_or_b64 exec, exec, s[2:3]
	v_or_b32_e32 v45, 32, v5
	v_or_b32_e32 v0, v4, v45
	v_lshlrev_b32_e32 v162, 2, v0
	v_lshl_add_u64 v[0:1], v[52:53], 0, v[162:163]
	v_mov_b32_e32 v12, 0
	v_mov_b32_e32 v16, 0
	s_and_saveexec_b64 s[2:3], vcc
	s_cbranch_execz .LBB0_732
	global_load_dword v182, v[0:1], off
.LBB0_732:
	s_or_b64 exec, exec, s[2:3]
	s_and_saveexec_b64 s[2:3], vcc
	s_cbranch_execz .LBB0_734
	global_load_dword v183, v[0:1], off offset:4
.LBB0_734:
	s_or_b64 exec, exec, s[2:3]
	v_or_b32_e32 v0, v6, v45
	v_lshlrev_b32_e32 v162, 2, v0
	v_lshl_add_u64 v[0:1], v[52:53], 0, v[162:163]
	v_mov_b32_e32 v17, 0
	v_mov_b32_e32 v38, 0
	s_and_saveexec_b64 s[2:3], vcc
	s_cbranch_execz .LBB0_736
	global_load_dword v184, v[0:1], off
.LBB0_736:
	s_or_b64 exec, exec, s[2:3]
	s_and_saveexec_b64 s[2:3], vcc
	s_cbranch_execz .LBB0_738
	global_load_dword v185, v[0:1], off offset:4
.LBB0_738:
	s_or_b64 exec, exec, s[2:3]
	v_or_b32_e32 v0, v7, v45
	v_lshlrev_b32_e32 v162, 2, v0
	v_lshl_add_u64 v[0:1], v[52:53], 0, v[162:163]
	v_mov_b32_e32 v18, 0
	v_mov_b32_e32 v39, 0
	s_and_saveexec_b64 s[2:3], vcc
	s_cbranch_execz .LBB0_740
	global_load_dword v186, v[0:1], off
.LBB0_740:
	s_or_b64 exec, exec, s[2:3]
	s_and_saveexec_b64 s[2:3], vcc
	s_cbranch_execz .LBB0_742
	global_load_dword v187, v[0:1], off offset:4
.LBB0_742:
	s_or_b64 exec, exec, s[2:3]
	v_or_b32_e32 v0, v8, v45
	v_lshlrev_b32_e32 v162, 2, v0
	v_lshl_add_u64 v[0:1], v[52:53], 0, v[162:163]
	v_mov_b32_e32 v19, 0
	v_mov_b32_e32 v40, 0
	s_and_saveexec_b64 s[2:3], vcc
	s_cbranch_execz .LBB0_744
	global_load_dword v190, v[0:1], off
.LBB0_744:
	s_or_b64 exec, exec, s[2:3]
	s_and_saveexec_b64 s[2:3], vcc
	s_cbranch_execz .LBB0_746
	global_load_dword v191, v[0:1], off offset:4
.LBB0_746:
	s_or_b64 exec, exec, s[2:3]
	v_or_b32_e32 v0, v9, v45
	v_lshlrev_b32_e32 v162, 2, v0
	v_lshl_add_u64 v[0:1], v[52:53], 0, v[162:163]
	v_mov_b32_e32 v14, 0
	v_mov_b32_e32 v41, 0
	s_and_saveexec_b64 s[2:3], vcc
	s_cbranch_execz .LBB0_748
	global_load_dword v192, v[0:1], off
.LBB0_748:
	s_or_b64 exec, exec, s[2:3]
	s_and_saveexec_b64 s[2:3], vcc
	s_cbranch_execz .LBB0_750
	global_load_dword v193, v[0:1], off offset:4
.LBB0_750:
	s_or_b64 exec, exec, s[2:3]
	v_or_b32_e32 v0, v10, v45
	v_lshlrev_b32_e32 v162, 2, v0
	v_lshl_add_u64 v[0:1], v[52:53], 0, v[162:163]
	v_mov_b32_e32 v43, 0
	v_mov_b32_e32 v42, 0
	s_and_saveexec_b64 s[2:3], vcc
	s_cbranch_execz .LBB0_752
	global_load_dword v198, v[0:1], off
.LBB0_752:
	s_or_b64 exec, exec, s[2:3]
	s_and_saveexec_b64 s[2:3], vcc
	s_cbranch_execz .LBB0_754
	global_load_dword v199, v[0:1], off offset:4
.LBB0_754:
	s_or_b64 exec, exec, s[2:3]
	v_or_b32_e32 v0, v11, v45
	v_lshlrev_b32_e32 v162, 2, v0
	v_lshl_add_u64 v[0:1], v[52:53], 0, v[162:163]
	v_mov_b32_e32 v15, 0
	v_mov_b32_e32 v44, 0
	s_and_saveexec_b64 s[2:3], vcc
	s_cbranch_execz .LBB0_756
	global_load_dword v200, v[0:1], off
.LBB0_756:
	s_or_b64 exec, exec, s[2:3]
	s_and_saveexec_b64 s[2:3], vcc
	s_cbranch_execz .LBB0_758
	global_load_dword v201, v[0:1], off offset:4
.LBB0_758:
	s_or_b64 exec, exec, s[2:3]
	v_or_b32_e32 v0, v13, v45
	v_lshlrev_b32_e32 v162, 2, v0
	v_lshl_add_u64 v[0:1], v[52:53], 0, v[162:163]
	v_mov_b32_e32 v46, 0
	v_mov_b32_e32 v45, 0
	s_and_saveexec_b64 s[2:3], vcc
	s_cbranch_execz .LBB0_760
	global_load_dword v202, v[0:1], off
.LBB0_760:
	s_or_b64 exec, exec, s[2:3]
	s_and_saveexec_b64 s[2:3], vcc
	s_cbranch_execz .LBB0_762
	global_load_dword v203, v[0:1], off offset:4
.LBB0_762:
	s_or_b64 exec, exec, s[2:3]
	v_or_b32_e32 v58, 64, v5
	v_or_b32_e32 v0, v4, v58
	v_lshlrev_b32_e32 v162, 2, v0
	v_lshl_add_u64 v[0:1], v[52:53], 0, v[162:163]
	v_mov_b32_e32 v56, 0
	v_mov_b32_e32 v47, 0
	s_and_saveexec_b64 s[2:3], vcc
	s_cbranch_execz .LBB0_764
	global_load_dword v204, v[0:1], off
.LBB0_764:
	s_or_b64 exec, exec, s[2:3]
	s_and_saveexec_b64 s[2:3], vcc
	s_cbranch_execz .LBB0_766
	global_load_dword v205, v[0:1], off offset:4
.LBB0_766:
	s_or_b64 exec, exec, s[2:3]
	v_or_b32_e32 v0, v6, v58
	v_lshlrev_b32_e32 v162, 2, v0
	v_lshl_add_u64 v[0:1], v[52:53], 0, v[162:163]
	v_mov_b32_e32 v62, 0
	v_mov_b32_e32 v57, 0
	s_and_saveexec_b64 s[2:3], vcc
	s_cbranch_execz .LBB0_768
	global_load_dword v206, v[0:1], off
.LBB0_768:
	s_or_b64 exec, exec, s[2:3]
	s_and_saveexec_b64 s[2:3], vcc
	s_cbranch_execz .LBB0_770
	global_load_dword v207, v[0:1], off offset:4
.LBB0_770:
	s_or_b64 exec, exec, s[2:3]
	v_or_b32_e32 v0, v7, v58
	v_lshlrev_b32_e32 v162, 2, v0
	v_lshl_add_u64 v[0:1], v[52:53], 0, v[162:163]
	v_mov_b32_e32 v70, 0
	v_mov_b32_e32 v68, 0
	s_and_saveexec_b64 s[2:3], vcc
	s_cbranch_execz .LBB0_772
	global_load_dword v208, v[0:1], off
.LBB0_772:
	s_or_b64 exec, exec, s[2:3]
	s_and_saveexec_b64 s[2:3], vcc
	s_cbranch_execz .LBB0_774
	global_load_dword v209, v[0:1], off offset:4
.LBB0_774:
	s_or_b64 exec, exec, s[2:3]
	v_or_b32_e32 v0, v8, v58
	v_lshlrev_b32_e32 v162, 2, v0
	v_lshl_add_u64 v[0:1], v[52:53], 0, v[162:163]
	v_mov_b32_e32 v74, 0
	v_mov_b32_e32 v73, 0
	s_and_saveexec_b64 s[2:3], vcc
	s_cbranch_execz .LBB0_776
	global_load_dword v210, v[0:1], off
.LBB0_776:
	s_or_b64 exec, exec, s[2:3]
	s_and_saveexec_b64 s[2:3], vcc
	s_cbranch_execz .LBB0_778
	global_load_dword v211, v[0:1], off offset:4
.LBB0_778:
	s_or_b64 exec, exec, s[2:3]
	v_or_b32_e32 v0, v9, v58
	v_lshlrev_b32_e32 v162, 2, v0
	v_lshl_add_u64 v[0:1], v[52:53], 0, v[162:163]
	v_mov_b32_e32 v78, 0
	v_mov_b32_e32 v77, 0
	s_and_saveexec_b64 s[2:3], vcc
	s_cbranch_execz .LBB0_780
	global_load_dword v212, v[0:1], off
.LBB0_780:
	s_or_b64 exec, exec, s[2:3]
	s_and_saveexec_b64 s[2:3], vcc
	s_cbranch_execz .LBB0_782
	global_load_dword v213, v[0:1], off offset:4
.LBB0_782:
	s_or_b64 exec, exec, s[2:3]
	v_or_b32_e32 v0, v10, v58
	v_lshlrev_b32_e32 v162, 2, v0
	v_lshl_add_u64 v[0:1], v[52:53], 0, v[162:163]
	v_mov_b32_e32 v82, 0
	v_mov_b32_e32 v81, 0
	s_and_saveexec_b64 s[2:3], vcc
	s_cbranch_execz .LBB0_784
	global_load_dword v214, v[0:1], off
.LBB0_784:
	s_or_b64 exec, exec, s[2:3]
	s_and_saveexec_b64 s[2:3], vcc
	s_cbranch_execz .LBB0_786
	global_load_dword v215, v[0:1], off offset:4
.LBB0_786:
	s_or_b64 exec, exec, s[2:3]
	v_or_b32_e32 v0, v11, v58
	v_lshlrev_b32_e32 v162, 2, v0
	v_lshl_add_u64 v[0:1], v[52:53], 0, v[162:163]
	v_mov_b32_e32 v86, 0
	v_mov_b32_e32 v85, 0
	s_and_saveexec_b64 s[2:3], vcc
	s_cbranch_execz .LBB0_788
	global_load_dword v216, v[0:1], off
.LBB0_788:
	s_or_b64 exec, exec, s[2:3]
	s_and_saveexec_b64 s[2:3], vcc
	s_cbranch_execz .LBB0_790
	global_load_dword v217, v[0:1], off offset:4
.LBB0_790:
	s_or_b64 exec, exec, s[2:3]
	v_or_b32_e32 v0, v13, v58
	v_lshlrev_b32_e32 v162, 2, v0
	v_lshl_add_u64 v[0:1], v[52:53], 0, v[162:163]
	v_mov_b32_e32 v88, 0
	v_mov_b32_e32 v87, 0
	s_and_saveexec_b64 s[2:3], vcc
	s_cbranch_execz .LBB0_792
	global_load_dword v218, v[0:1], off
.LBB0_792:
	s_or_b64 exec, exec, s[2:3]
	s_and_saveexec_b64 s[2:3], vcc
	s_cbranch_execz .LBB0_794
	global_load_dword v219, v[0:1], off offset:4
.LBB0_794:
	s_or_b64 exec, exec, s[2:3]
	v_or_b32_e32 v5, 0x60, v5
	v_or_b32_e32 v0, v4, v5
	v_lshlrev_b32_e32 v162, 2, v0
	v_lshl_add_u64 v[0:1], v[52:53], 0, v[162:163]
	v_mov_b32_e32 v59, 0
	v_mov_b32_e32 v58, 0
	s_and_saveexec_b64 s[2:3], vcc
	s_cbranch_execz .LBB0_796
	global_load_dword v220, v[0:1], off
.LBB0_796:
	s_or_b64 exec, exec, s[2:3]
	s_and_saveexec_b64 s[2:3], vcc
	s_cbranch_execz .LBB0_798
	global_load_dword v221, v[0:1], off offset:4
.LBB0_798:
	s_or_b64 exec, exec, s[2:3]
	v_or_b32_e32 v0, v6, v5
	v_lshlrev_b32_e32 v162, 2, v0
	v_lshl_add_u64 v[0:1], v[52:53], 0, v[162:163]
	v_mov_b32_e32 v64, 0
	v_mov_b32_e32 v63, 0
	s_and_saveexec_b64 s[2:3], vcc
	s_cbranch_execz .LBB0_800
	global_load_dword v222, v[0:1], off
.LBB0_800:
	s_or_b64 exec, exec, s[2:3]
	s_and_saveexec_b64 s[2:3], vcc
	s_cbranch_execz .LBB0_802
	global_load_dword v223, v[0:1], off offset:4
.LBB0_802:
	s_or_b64 exec, exec, s[2:3]
	v_or_b32_e32 v0, v7, v5
	v_lshlrev_b32_e32 v162, 2, v0
	v_lshl_add_u64 v[0:1], v[52:53], 0, v[162:163]
	v_mov_b32_e32 v66, 0
	v_mov_b32_e32 v65, 0
	s_and_saveexec_b64 s[2:3], vcc
	s_cbranch_execz .LBB0_804
	global_load_dword v224, v[0:1], off
.LBB0_804:
	s_or_b64 exec, exec, s[2:3]
	s_and_saveexec_b64 s[2:3], vcc
	s_cbranch_execz .LBB0_806
	global_load_dword v225, v[0:1], off offset:4
.LBB0_806:
	s_or_b64 exec, exec, s[2:3]
	v_or_b32_e32 v0, v8, v5
	v_lshlrev_b32_e32 v162, 2, v0
	v_lshl_add_u64 v[0:1], v[52:53], 0, v[162:163]
	v_mov_b32_e32 v69, 0
	v_mov_b32_e32 v67, 0
	s_and_saveexec_b64 s[2:3], vcc
	s_cbranch_execz .LBB0_808
	global_load_dword v226, v[0:1], off
.LBB0_808:
	s_or_b64 exec, exec, s[2:3]
	s_and_saveexec_b64 s[2:3], vcc
	s_cbranch_execz .LBB0_810
	global_load_dword v227, v[0:1], off offset:4
.LBB0_810:
	s_or_b64 exec, exec, s[2:3]
	v_or_b32_e32 v0, v9, v5
	v_lshlrev_b32_e32 v162, 2, v0
	v_lshl_add_u64 v[0:1], v[52:53], 0, v[162:163]
	v_mov_b32_e32 v72, 0
	v_mov_b32_e32 v71, 0
	s_and_saveexec_b64 s[2:3], vcc
	s_cbranch_execz .LBB0_812
	global_load_dword v228, v[0:1], off
.LBB0_812:
	s_or_b64 exec, exec, s[2:3]
	s_and_saveexec_b64 s[2:3], vcc
	s_cbranch_execz .LBB0_814
	global_load_dword v229, v[0:1], off offset:4
.LBB0_814:
	s_or_b64 exec, exec, s[2:3]
	v_or_b32_e32 v0, v10, v5
	v_lshlrev_b32_e32 v162, 2, v0
	v_lshl_add_u64 v[0:1], v[52:53], 0, v[162:163]
	v_mov_b32_e32 v76, 0
	v_mov_b32_e32 v75, 0
	s_and_saveexec_b64 s[2:3], vcc
	s_cbranch_execz .LBB0_816
	global_load_dword v230, v[0:1], off
.LBB0_816:
	s_or_b64 exec, exec, s[2:3]
	s_and_saveexec_b64 s[2:3], vcc
	s_cbranch_execz .LBB0_818
	global_load_dword v231, v[0:1], off offset:4
.LBB0_818:
	s_or_b64 exec, exec, s[2:3]
	v_or_b32_e32 v0, v11, v5
	v_lshlrev_b32_e32 v162, 2, v0
	v_lshl_add_u64 v[0:1], v[52:53], 0, v[162:163]
	v_mov_b32_e32 v80, 0
	v_mov_b32_e32 v79, 0
	s_and_saveexec_b64 s[2:3], vcc
	s_cbranch_execz .LBB0_820
	global_load_dword v232, v[0:1], off
.LBB0_820:
	s_or_b64 exec, exec, s[2:3]
	s_and_saveexec_b64 s[2:3], vcc
	s_cbranch_execz .LBB0_822
	global_load_dword v233, v[0:1], off offset:4
.LBB0_822:
	s_or_b64 exec, exec, s[2:3]
	v_or_b32_e32 v0, v13, v5
	v_lshlrev_b32_e32 v162, 2, v0
	v_lshl_add_u64 v[0:1], v[52:53], 0, v[162:163]
	v_mov_b32_e32 v84, 0
	v_mov_b32_e32 v83, 0
	s_and_saveexec_b64 s[2:3], vcc
	s_cbranch_execz .LBB0_824
	global_load_dword v234, v[0:1], off
.LBB0_824:
	s_or_b64 exec, exec, s[2:3]
	s_and_saveexec_b64 s[2:3], vcc
	s_cbranch_execz .LBB0_826
	global_load_dword v235, v[0:1], off offset:4
.LBB0_826:
	s_or_b64 exec, exec, s[2:3]
	s_waitcnt vmcnt(0)
	s_and_saveexec_b64 s[2:3], vcc
	v_cvt_pk_bf16_f32 v24, v164, s0
	v_cvt_pk_bf16_f32 v20, v165, s0
	v_cvt_pk_bf16_f32 v30, v166, s0
	v_cvt_pk_bf16_f32 v25, v167, s0
	v_cvt_pk_bf16_f32 v31, v170, s0
	v_cvt_pk_bf16_f32 v21, v171, s0
	v_cvt_pk_bf16_f32 v32, v172, s0
	v_cvt_pk_bf16_f32 v26, v173, s0
	v_cvt_pk_bf16_f32 v33, v174, s0
	v_cvt_pk_bf16_f32 v22, v175, s0
	v_cvt_pk_bf16_f32 v34, v176, s0
	v_cvt_pk_bf16_f32 v27, v177, s0
	v_cvt_pk_bf16_f32 v35, v178, s0
	v_cvt_pk_bf16_f32 v23, v179, s0
	v_cvt_pk_bf16_f32 v36, v180, s0
	v_cvt_pk_bf16_f32 v37, v181, s0
	v_cvt_pk_bf16_f32 v16, v182, s0
	v_cvt_pk_bf16_f32 v12, v183, s0
	v_cvt_pk_bf16_f32 v38, v184, s0
	v_cvt_pk_bf16_f32 v17, v185, s0
	v_cvt_pk_bf16_f32 v39, v186, s0
	v_cvt_pk_bf16_f32 v18, v187, s0
	v_cvt_pk_bf16_f32 v40, v190, s0
	v_cvt_pk_bf16_f32 v19, v191, s0
	v_cvt_pk_bf16_f32 v41, v192, s0
	v_cvt_pk_bf16_f32 v14, v193, s0
	v_cvt_pk_bf16_f32 v42, v198, s0
	v_cvt_pk_bf16_f32 v43, v199, s0
	v_cvt_pk_bf16_f32 v44, v200, s0
	v_cvt_pk_bf16_f32 v15, v201, s0
	v_cvt_pk_bf16_f32 v45, v202, s0
	v_cvt_pk_bf16_f32 v46, v203, s0
	v_cvt_pk_bf16_f32 v47, v204, s0
	v_cvt_pk_bf16_f32 v56, v205, s0
	v_cvt_pk_bf16_f32 v57, v206, s0
	v_cvt_pk_bf16_f32 v62, v207, s0
	v_cvt_pk_bf16_f32 v68, v208, s0
	v_cvt_pk_bf16_f32 v70, v209, s0
	v_cvt_pk_bf16_f32 v73, v210, s0
	v_cvt_pk_bf16_f32 v74, v211, s0
	v_cvt_pk_bf16_f32 v77, v212, s0
	v_cvt_pk_bf16_f32 v78, v213, s0
	v_cvt_pk_bf16_f32 v81, v214, s0
	v_cvt_pk_bf16_f32 v82, v215, s0
	v_cvt_pk_bf16_f32 v85, v216, s0
	v_cvt_pk_bf16_f32 v86, v217, s0
	v_cvt_pk_bf16_f32 v87, v218, s0
	v_cvt_pk_bf16_f32 v88, v219, s0
	v_cvt_pk_bf16_f32 v58, v220, s0
	v_cvt_pk_bf16_f32 v59, v221, s0
	v_cvt_pk_bf16_f32 v63, v222, s0
	v_cvt_pk_bf16_f32 v64, v223, s0
	v_cvt_pk_bf16_f32 v65, v224, s0
	v_cvt_pk_bf16_f32 v66, v225, s0
	v_cvt_pk_bf16_f32 v67, v226, s0
	v_cvt_pk_bf16_f32 v69, v227, s0
	v_cvt_pk_bf16_f32 v71, v228, s0
	v_cvt_pk_bf16_f32 v72, v229, s0
	v_cvt_pk_bf16_f32 v75, v230, s0
	v_cvt_pk_bf16_f32 v76, v231, s0
	v_cvt_pk_bf16_f32 v79, v232, s0
	v_cvt_pk_bf16_f32 v80, v233, s0
	v_cvt_pk_bf16_f32 v83, v234, s0
	v_cvt_pk_bf16_f32 v84, v235, s0
	s_or_b64 exec, exec, s[2:3]
	v_ashrrev_i32_e32 v0, 5, v29
	s_mov_b32 s2, 0xfe03f81
	s_mov_b32 s4, 0x5040100
	v_mul_hi_i32 v1, v0, s2
	v_perm_b32 v24, v30, v24, s4
	v_lshrrev_b32_e32 v30, 31, v1
	v_ashrrev_i32_e32 v1, 4, v1
	v_add_u32_e32 v30, v1, v30
	v_mul_i32_i24_e32 v1, 0x102, v30
	v_sub_u32_e32 v0, v0, v1
	v_ashrrev_i32_e32 v1, 31, v0
	v_mul_i32_i24_e32 v30, 0x4080, v30
	v_perm_b32 v20, v25, v20, s4
	v_perm_b32 v25, v32, v31, s4
	v_lshlrev_b64 v[0:1], 6, v[0:1]
	v_ashrrev_i32_e32 v31, 31, v30
	v_mov_b32_e32 v32, v160
	v_lshl_add_u64 v[0:1], v[0:1], 0, v[30:31]
	v_perm_b32 v8, v57, v47, s4
	v_and_or_b32 v0, v32, 63, v0
	v_mad_u64_u32 v[30:31], s[2:3], v0, s97, v[48:49]
	v_lshlrev_b32_e32 v0, 5, v29
	v_mad_i32_i24 v31, v1, s97, v31
	v_and_b32_e32 v162, 0x3e0, v0
	v_lshl_add_u64 v[0:1], v[30:31], 0, v[162:163]
	v_perm_b32 v15, v46, v15, s4
	v_perm_b32 v14, v43, v14, s4
	v_perm_b32 v13, v19, v18, s4
	v_perm_b32 v12, v17, v12, s4
	v_perm_b32 v19, v45, v44, s4
	v_perm_b32 v18, v42, v41, s4
	v_perm_b32 v17, v40, v39, s4
	global_load_dwordx4 v[40:43], v[0:1], off offset:3600
	global_load_dwordx4 v[44:47], v[0:1], off offset:3584
	s_movk_i32 s2, 0x3300
	v_mul_lo_u32 v0, v28, s2
	s_mov_b64 s[2:3], 0x1e422000
	v_perm_b32 v7, v88, v86, s4
	v_perm_b32 v6, v82, v78, s4
	v_perm_b32 v5, v74, v70, s4
	v_perm_b32 v4, v62, v56, s4
	v_perm_b32 v11, v87, v85, s4
	v_perm_b32 v10, v81, v77, s4
	v_perm_b32 v9, v73, v68, s4
	v_perm_b32 v16, v38, v16, s4
	v_perm_b32 v23, v37, v23, s4
	v_perm_b32 v22, v27, v22, s4
	v_perm_b32 v21, v26, v21, s4
	v_perm_b32 v27, v36, v35, s4
	v_perm_b32 v26, v34, v33, s4
	v_add_u32_e32 v62, 0x100, v0
	v_lshl_add_u64 v[56:57], v[2:3], 0, s[2:3]
	v_perm_b32 v28, v64, v59, s4
	v_perm_b32 v29, v69, v66, s4
	v_perm_b32 v30, v76, v72, s4
	v_perm_b32 v31, v84, v80, s4
	v_perm_b32 v0, v63, v58, s4
	v_perm_b32 v1, v67, v65, s4
	v_perm_b32 v2, v75, v71, s4
	v_perm_b32 v3, v83, v79, s4

.LBB0_1022:
	s_andn2_b64 vcc, exec, s[2:3]
	s_cbranch_vccnz .LBB0_1084
	s_mov_b64 s[2:3], s[40:41]
	s_waitcnt vmcnt(0) lgkmcnt(0)
	v_mov_b64_e32 v[0:1], s[2:3]
	s_waitcnt lgkmcnt(0)
	flat_load_dwordx2 v[2:3], v[0:1] offset:248
	v_mov_b32_e32 v0, v160
	v_readlane_b32 s2, v253, 0
	v_ashrrev_i32_e32 v1, 6, v0
	s_nop 0
	v_lshl_add_u32 v4, v1, 6, s2
	v_cmp_gt_i32_e32 vcc, 64, v4
	s_and_saveexec_b64 s[2:3], vcc
	s_cbranch_execz .LBB0_1026
	v_lshlrev_b32_e32 v0, 3, v0
	v_and_b32_e32 v10, 31, v4
	v_readlane_b32 s4, v255, 24
	v_mov_b32_e32 v1, 0x48000
	v_and_b32_e32 v8, 0x1f8, v0
	s_waitcnt vmcnt(0) lgkmcnt(0)
	v_mad_i64_i32 v[6:7], s[4:5], s4, v1, v[2:3]
	v_lshl_or_b32 v162, v10, 9, v8
	v_lshl_add_u64 v[0:1], v[6:7], 0, v[162:163]
	v_add_co_u32_e32 v0, vcc, 0x1ec36000, v0
	v_lshrrev_b32_e32 v4, 5, v4
	s_nop 0
	v_addc_co_u32_e32 v1, vcc, 0, v1, vcc
	global_load_dwordx2 v[0:1], v[0:1], off
	v_mov_b32_e32 v9, v163
	s_movk_i32 s5, 0x2040
	v_mul_lo_u32 v6, v4, s5
	v_lshl_add_u64 v[4:5], v[2:3], 0, v[8:9]
	s_mov_b64 s[6:7], 0x1e422000
	v_mov_b32_e32 v14, 0
	v_or_b32_e32 v6, v6, v10
	v_lshl_add_u64 v[2:3], v[4:5], 0, s[6:7]
	s_mov_b64 s[6:7], 0x1ecc6000
	s_movk_i32 s4, 0xffd5
	v_lshl_add_u64 v[4:5], v[4:5], 0, s[6:7]
	v_add_u32_e32 v6, 0x540, v6
	v_mov_b32_e32 v15, v14
	s_waitcnt vmcnt(0)
	v_mov_b32_e32 v8, v0
	v_mov_b32_e32 v9, v0
	v_pk_mov_b32 v[10:11], v[0:1], v[0:1] op_sel:[1,0]
	v_mov_b32_e32 v12, v1
	v_mov_b32_e32 v13, v1

.LBB0_1110:
	s_cmpk_gt_u32 s95, 0xc17
	s_cbranch_scc1 .LBB0_1375
	v_ashrrev_i32_e32 v44, 6, v96
	v_add_u32_e32 v88, 0xffffdfc0, v44
	v_lshl_add_u32 v35, s95, 3, v88
	v_readlane_b32 s2, v255, 24
	v_mov_b32_e32 v8, 0x48000
	v_and_b32_e32 v89, 31, v35
	v_mov_b32_e32 v12, v160
	v_mad_i64_i32 v[8:9], s[2:3], s2, v8, v[2:3]
	s_mov_b64 s[2:3], 0x1ec32000
	v_and_b32_e32 v13, 63, v12
	v_lshlrev_b32_e32 v10, 9, v89
	v_lshl_add_u64 v[72:73], v[8:9], 0, s[2:3]
	v_lshl_or_b32 v162, v13, 3, v10
	v_lshl_add_u64 v[10:11], v[72:73], 0, v[162:163]
	global_load_dwordx2 v[76:77], v[10:11], off
	v_lshrrev_b32_e32 v34, 1, v12
	s_mov_b64 s[2:3], 0x1ec3a000
	v_lshlrev_b32_e32 v33, 4, v89
	v_and_b32_e32 v32, 15, v12
	v_lshl_add_u64 v[74:75], v[8:9], 0, s[2:3]
	v_and_or_b32 v8, v34, 8, v33
	v_lshlrev_b32_e32 v10, 7, v8
	v_lshlrev_b32_e32 v11, 1, v32
	v_or_b32_e32 v8, v10, v11
	v_lshlrev_b32_e32 v162, 2, v8
	v_cmp_gt_u32_e32 vcc, 32, v13
	v_lshl_add_u64 v[8:9], v[74:75], 0, v[162:163]
	v_mov_b32_e32 v24, 0
	v_mov_b32_e32 v28, 0
	s_and_saveexec_b64 s[2:3], vcc
	s_cbranch_execz .LBB0_1113
	global_load_dword v164, v[8:9], off
.LBB0_1113:
	s_or_b64 exec, exec, s[2:3]
	s_and_saveexec_b64 s[2:3], vcc
	s_cbranch_execz .LBB0_1115
	global_load_dword v165, v[8:9], off offset:4
.LBB0_1115:
	s_or_b64 exec, exec, s[2:3]
	v_or_b32_e32 v12, 0x80, v10
	v_or_b32_e32 v8, v12, v11
	v_lshlrev_b32_e32 v162, 2, v8
	v_lshl_add_u64 v[8:9], v[74:75], 0, v[162:163]
	v_mov_b32_e32 v29, 0
	v_mov_b32_e32 v36, 0
	s_and_saveexec_b64 s[2:3], vcc
	s_cbranch_execz .LBB0_1117
	global_load_dword v166, v[8:9], off
.LBB0_1117:
	s_or_b64 exec, exec, s[2:3]
	s_and_saveexec_b64 s[2:3], vcc
	s_cbranch_execz .LBB0_1119
	global_load_dword v167, v[8:9], off offset:4
.LBB0_1119:
	s_or_b64 exec, exec, s[2:3]
	v_or_b32_e32 v13, 0x100, v10
	v_or_b32_e32 v8, v13, v11
	v_lshlrev_b32_e32 v162, 2, v8
	v_lshl_add_u64 v[8:9], v[74:75], 0, v[162:163]
	v_mov_b32_e32 v25, 0
	v_mov_b32_e32 v37, 0
	s_and_saveexec_b64 s[2:3], vcc
	s_cbranch_execz .LBB0_1121
	global_load_dword v170, v[8:9], off
.LBB0_1121:
	s_or_b64 exec, exec, s[2:3]
	s_and_saveexec_b64 s[2:3], vcc
	s_cbranch_execz .LBB0_1123
	global_load_dword v171, v[8:9], off offset:4
.LBB0_1123:
	s_or_b64 exec, exec, s[2:3]
	v_or_b32_e32 v14, 0x180, v10
	v_or_b32_e32 v8, v14, v11
	v_lshlrev_b32_e32 v162, 2, v8
	v_lshl_add_u64 v[8:9], v[74:75], 0, v[162:163]
	v_mov_b32_e32 v30, 0
	v_mov_b32_e32 v38, 0
	s_and_saveexec_b64 s[2:3], vcc
	s_cbranch_execz .LBB0_1125
	global_load_dword v172, v[8:9], off
.LBB0_1125:
	s_or_b64 exec, exec, s[2:3]
	s_and_saveexec_b64 s[2:3], vcc
	s_cbranch_execz .LBB0_1127
	global_load_dword v173, v[8:9], off offset:4
.LBB0_1127:
	s_or_b64 exec, exec, s[2:3]
	v_or_b32_e32 v15, 0x200, v10
	v_or_b32_e32 v8, v15, v11
	v_lshlrev_b32_e32 v162, 2, v8
	v_lshl_add_u64 v[8:9], v[74:75], 0, v[162:163]
	v_mov_b32_e32 v26, 0
	v_mov_b32_e32 v39, 0
	s_and_saveexec_b64 s[2:3], vcc
	s_cbranch_execz .LBB0_1129
	global_load_dword v174, v[8:9], off
.LBB0_1129:
	s_or_b64 exec, exec, s[2:3]
	s_and_saveexec_b64 s[2:3], vcc
	s_cbranch_execz .LBB0_1131
	global_load_dword v175, v[8:9], off offset:4
.LBB0_1131:
	s_or_b64 exec, exec, s[2:3]
	v_or_b32_e32 v16, 0x280, v10
	v_or_b32_e32 v8, v16, v11
	v_lshlrev_b32_e32 v162, 2, v8
	v_lshl_add_u64 v[8:9], v[74:75], 0, v[162:163]
	v_mov_b32_e32 v31, 0
	v_mov_b32_e32 v40, 0
	s_and_saveexec_b64 s[2:3], vcc
	s_cbranch_execz .LBB0_1133
	global_load_dword v176, v[8:9], off
.LBB0_1133:
	s_or_b64 exec, exec, s[2:3]
	s_and_saveexec_b64 s[2:3], vcc
	s_cbranch_execz .LBB0_1135
	global_load_dword v177, v[8:9], off offset:4
.LBB0_1135:
	s_or_b64 exec, exec, s[2:3]
	v_or_b32_e32 v17, 0x300, v10
	v_or_b32_e32 v8, v17, v11
	v_lshlrev_b32_e32 v162, 2, v8
	v_lshl_add_u64 v[8:9], v[74:75], 0, v[162:163]
	v_mov_b32_e32 v27, 0
	v_mov_b32_e32 v41, 0
	s_and_saveexec_b64 s[2:3], vcc
	s_cbranch_execz .LBB0_1137
	global_load_dword v178, v[8:9], off
.LBB0_1137:
	s_or_b64 exec, exec, s[2:3]
	s_and_saveexec_b64 s[2:3], vcc
	s_cbranch_execz .LBB0_1139
	global_load_dword v179, v[8:9], off offset:4
.LBB0_1139:
	s_or_b64 exec, exec, s[2:3]
	v_or_b32_e32 v18, 0x380, v10
	v_or_b32_e32 v8, v18, v11
	v_lshlrev_b32_e32 v162, 2, v8
	v_lshl_add_u64 v[8:9], v[74:75], 0, v[162:163]
	v_mov_b32_e32 v43, 0
	v_mov_b32_e32 v42, 0
	s_and_saveexec_b64 s[2:3], vcc
	s_cbranch_execz .LBB0_1141
	global_load_dword v180, v[8:9], off
.LBB0_1141:
	s_or_b64 exec, exec, s[2:3]
	s_and_saveexec_b64 s[2:3], vcc
	s_cbranch_execz .LBB0_1143
	global_load_dword v181, v[8:9], off offset:4
.LBB0_1143:
	s_or_b64 exec, exec, s[2:3]
	v_or_b32_e32 v52, 32, v11
	v_or_b32_e32 v8, v10, v52
	v_lshlrev_b32_e32 v162, 2, v8
	v_lshl_add_u64 v[8:9], v[74:75], 0, v[162:163]
	v_mov_b32_e32 v21, 0
	v_mov_b32_e32 v20, 0
	s_and_saveexec_b64 s[2:3], vcc
	s_cbranch_execz .LBB0_1145
	global_load_dword v182, v[8:9], off
.LBB0_1145:
	s_or_b64 exec, exec, s[2:3]
	s_and_saveexec_b64 s[2:3], vcc
	s_cbranch_execz .LBB0_1147
	global_load_dword v183, v[8:9], off offset:4
.LBB0_1147:
	s_or_b64 exec, exec, s[2:3]
	v_or_b32_e32 v8, v12, v52
	v_lshlrev_b32_e32 v162, 2, v8
	v_lshl_add_u64 v[8:9], v[74:75], 0, v[162:163]
	v_mov_b32_e32 v22, 0
	v_mov_b32_e32 v45, 0
	s_and_saveexec_b64 s[2:3], vcc
	s_cbranch_execz .LBB0_1149
	global_load_dword v184, v[8:9], off
.LBB0_1149:
	s_or_b64 exec, exec, s[2:3]
	s_and_saveexec_b64 s[2:3], vcc
	s_cbranch_execz .LBB0_1151
	global_load_dword v185, v[8:9], off offset:4
.LBB0_1151:
	s_or_b64 exec, exec, s[2:3]
	v_or_b32_e32 v8, v13, v52
	v_lshlrev_b32_e32 v162, 2, v8
	v_lshl_add_u64 v[8:9], v[74:75], 0, v[162:163]
	v_mov_b32_e32 v23, 0
	v_mov_b32_e32 v46, 0
	s_and_saveexec_b64 s[2:3], vcc
	s_cbranch_execz .LBB0_1153
	global_load_dword v186, v[8:9], off
.LBB0_1153:
	s_or_b64 exec, exec, s[2:3]
	s_and_saveexec_b64 s[2:3], vcc
	s_cbranch_execz .LBB0_1155
	global_load_dword v187, v[8:9], off offset:4
.LBB0_1155:
	s_or_b64 exec, exec, s[2:3]
	v_or_b32_e32 v8, v14, v52
	v_lshlrev_b32_e32 v162, 2, v8
	v_lshl_add_u64 v[8:9], v[74:75], 0, v[162:163]
	v_mov_b32_e32 v48, 0
	v_mov_b32_e32 v47, 0
	s_and_saveexec_b64 s[2:3], vcc
	s_cbranch_execz .LBB0_1157
	global_load_dword v190, v[8:9], off
.LBB0_1157:
	s_or_b64 exec, exec, s[2:3]
	s_and_saveexec_b64 s[2:3], vcc
	s_cbranch_execz .LBB0_1159
	global_load_dword v191, v[8:9], off offset:4
.LBB0_1159:
	s_or_b64 exec, exec, s[2:3]
	v_or_b32_e32 v8, v15, v52
	v_lshlrev_b32_e32 v162, 2, v8
	v_lshl_add_u64 v[8:9], v[74:75], 0, v[162:163]
	v_mov_b32_e32 v50, 0
	v_mov_b32_e32 v49, 0
	s_and_saveexec_b64 s[2:3], vcc
	s_cbranch_execz .LBB0_1161
	global_load_dword v192, v[8:9], off
.LBB0_1161:
	s_or_b64 exec, exec, s[2:3]
	s_and_saveexec_b64 s[2:3], vcc
	s_cbranch_execz .LBB0_1163
	global_load_dword v193, v[8:9], off offset:4
.LBB0_1163:
	s_or_b64 exec, exec, s[2:3]
	v_or_b32_e32 v8, v16, v52
	v_lshlrev_b32_e32 v162, 2, v8
	v_lshl_add_u64 v[8:9], v[74:75], 0, v[162:163]
	v_mov_b32_e32 v64, 0
	v_mov_b32_e32 v51, 0
	s_and_saveexec_b64 s[2:3], vcc
	s_cbranch_execz .LBB0_1165
	global_load_dword v198, v[8:9], off
.LBB0_1165:
	s_or_b64 exec, exec, s[2:3]
	s_and_saveexec_b64 s[2:3], vcc
	s_cbranch_execz .LBB0_1167
	global_load_dword v199, v[8:9], off offset:4
.LBB0_1167:
	s_or_b64 exec, exec, s[2:3]
	v_or_b32_e32 v8, v17, v52
	v_lshlrev_b32_e32 v162, 2, v8
	v_lshl_add_u64 v[8:9], v[74:75], 0, v[162:163]
	v_mov_b32_e32 v19, 0
	v_mov_b32_e32 v65, 0
	s_and_saveexec_b64 s[2:3], vcc
	s_cbranch_execz .LBB0_1169
	global_load_dword v200, v[8:9], off
.LBB0_1169:
	s_or_b64 exec, exec, s[2:3]
	s_and_saveexec_b64 s[2:3], vcc
	s_cbranch_execz .LBB0_1171
	global_load_dword v201, v[8:9], off offset:4
.LBB0_1171:
	s_or_b64 exec, exec, s[2:3]
	v_or_b32_e32 v8, v18, v52
	v_lshlrev_b32_e32 v162, 2, v8
	v_lshl_add_u64 v[8:9], v[74:75], 0, v[162:163]
	v_mov_b32_e32 v67, 0
	v_mov_b32_e32 v66, 0
	s_and_saveexec_b64 s[2:3], vcc
	s_cbranch_execz .LBB0_1173
	global_load_dword v202, v[8:9], off
.LBB0_1173:
	s_or_b64 exec, exec, s[2:3]
	s_and_saveexec_b64 s[2:3], vcc
	s_cbranch_execz .LBB0_1175
	global_load_dword v203, v[8:9], off offset:4
.LBB0_1175:
	s_or_b64 exec, exec, s[2:3]
	v_or_b32_e32 v52, 64, v11
	v_or_b32_e32 v8, v10, v52
	v_lshlrev_b32_e32 v162, 2, v8
	v_lshl_add_u64 v[8:9], v[74:75], 0, v[162:163]
	v_mov_b32_e32 v69, 0
	v_mov_b32_e32 v68, 0
	s_and_saveexec_b64 s[2:3], vcc
	s_cbranch_execz .LBB0_1177
	global_load_dword v204, v[8:9], off
.LBB0_1177:
	s_or_b64 exec, exec, s[2:3]
	s_and_saveexec_b64 s[2:3], vcc
	s_cbranch_execz .LBB0_1179
	global_load_dword v205, v[8:9], off offset:4
.LBB0_1179:
	s_or_b64 exec, exec, s[2:3]
	v_or_b32_e32 v8, v12, v52
	v_lshlrev_b32_e32 v162, 2, v8
	v_lshl_add_u64 v[8:9], v[74:75], 0, v[162:163]
	v_mov_b32_e32 v71, 0
	v_mov_b32_e32 v70, 0
	s_and_saveexec_b64 s[2:3], vcc
	s_cbranch_execz .LBB0_1181
	global_load_dword v206, v[8:9], off
.LBB0_1181:
	s_or_b64 exec, exec, s[2:3]
	s_and_saveexec_b64 s[2:3], vcc
	s_cbranch_execz .LBB0_1183
	global_load_dword v207, v[8:9], off offset:4
.LBB0_1183:
	s_or_b64 exec, exec, s[2:3]
	v_or_b32_e32 v8, v13, v52
	v_lshlrev_b32_e32 v162, 2, v8
	v_lshl_add_u64 v[8:9], v[74:75], 0, v[162:163]
	v_mov_b32_e32 v79, 0
	v_mov_b32_e32 v78, 0
	s_and_saveexec_b64 s[2:3], vcc
	s_cbranch_execz .LBB0_1185
	global_load_dword v208, v[8:9], off
.LBB0_1185:
	s_or_b64 exec, exec, s[2:3]
	s_and_saveexec_b64 s[2:3], vcc
	s_cbranch_execz .LBB0_1187
	global_load_dword v209, v[8:9], off offset:4
.LBB0_1187:
	s_or_b64 exec, exec, s[2:3]
	v_or_b32_e32 v8, v14, v52
	v_lshlrev_b32_e32 v162, 2, v8
	v_lshl_add_u64 v[8:9], v[74:75], 0, v[162:163]
	v_mov_b32_e32 v91, 0
	v_mov_b32_e32 v90, 0
	s_and_saveexec_b64 s[2:3], vcc
	s_cbranch_execz .LBB0_1189
	global_load_dword v210, v[8:9], off
.LBB0_1189:
	s_or_b64 exec, exec, s[2:3]
	s_and_saveexec_b64 s[2:3], vcc
	s_cbranch_execz .LBB0_1191
	global_load_dword v211, v[8:9], off offset:4
.LBB0_1191:
	s_or_b64 exec, exec, s[2:3]
	v_or_b32_e32 v8, v15, v52
	v_lshlrev_b32_e32 v162, 2, v8
	v_lshl_add_u64 v[8:9], v[74:75], 0, v[162:163]
	v_mov_b32_e32 v93, 0
	v_mov_b32_e32 v92, 0
	s_and_saveexec_b64 s[2:3], vcc
	s_cbranch_execz .LBB0_1193
	global_load_dword v212, v[8:9], off
.LBB0_1193:
	s_or_b64 exec, exec, s[2:3]
	s_and_saveexec_b64 s[2:3], vcc
	s_cbranch_execz .LBB0_1195
	global_load_dword v213, v[8:9], off offset:4
.LBB0_1195:
	s_or_b64 exec, exec, s[2:3]
	v_or_b32_e32 v8, v16, v52
	v_lshlrev_b32_e32 v162, 2, v8
	v_lshl_add_u64 v[8:9], v[74:75], 0, v[162:163]
	v_mov_b32_e32 v95, 0
	v_mov_b32_e32 v94, 0
	s_and_saveexec_b64 s[2:3], vcc
	s_cbranch_execz .LBB0_1197
	global_load_dword v214, v[8:9], off
.LBB0_1197:
	s_or_b64 exec, exec, s[2:3]
	s_and_saveexec_b64 s[2:3], vcc
	s_cbranch_execz .LBB0_1199
	global_load_dword v215, v[8:9], off offset:4
.LBB0_1199:
	s_or_b64 exec, exec, s[2:3]
	v_or_b32_e32 v8, v17, v52
	v_lshlrev_b32_e32 v162, 2, v8
	v_lshl_add_u64 v[8:9], v[74:75], 0, v[162:163]
	v_mov_b32_e32 v98, 0
	v_mov_b32_e32 v97, 0
	s_and_saveexec_b64 s[2:3], vcc
	s_cbranch_execz .LBB0_1201
	global_load_dword v216, v[8:9], off
.LBB0_1201:
	s_or_b64 exec, exec, s[2:3]
	s_and_saveexec_b64 s[2:3], vcc
	s_cbranch_execz .LBB0_1203
	global_load_dword v217, v[8:9], off offset:4
.LBB0_1203:
	s_or_b64 exec, exec, s[2:3]
	v_or_b32_e32 v8, v18, v52
	v_lshlrev_b32_e32 v162, 2, v8
	v_lshl_add_u64 v[8:9], v[74:75], 0, v[162:163]
	v_mov_b32_e32 v100, 0
	v_mov_b32_e32 v99, 0
	s_and_saveexec_b64 s[2:3], vcc
	s_cbranch_execz .LBB0_1205
	global_load_dword v218, v[8:9], off
.LBB0_1205:
	s_or_b64 exec, exec, s[2:3]
	s_and_saveexec_b64 s[2:3], vcc
	s_cbranch_execz .LBB0_1207
	global_load_dword v219, v[8:9], off offset:4
.LBB0_1207:
	s_or_b64 exec, exec, s[2:3]
	v_or_b32_e32 v11, 0x60, v11
	v_or_b32_e32 v8, v10, v11
	v_lshlrev_b32_e32 v162, 2, v8
	v_lshl_add_u64 v[8:9], v[74:75], 0, v[162:163]
	v_mov_b32_e32 v52, 0
	v_mov_b32_e32 v56, 0
	s_and_saveexec_b64 s[2:3], vcc
	s_cbranch_execz .LBB0_1209
	global_load_dword v220, v[8:9], off
.LBB0_1209:
	s_or_b64 exec, exec, s[2:3]
	s_and_saveexec_b64 s[2:3], vcc
	s_cbranch_execz .LBB0_1211
	global_load_dword v221, v[8:9], off offset:4
.LBB0_1211:
	s_or_b64 exec, exec, s[2:3]
	v_or_b32_e32 v8, v12, v11
	v_lshlrev_b32_e32 v162, 2, v8
	v_lshl_add_u64 v[8:9], v[74:75], 0, v[162:163]
	v_mov_b32_e32 v53, 0
	v_mov_b32_e32 v57, 0
	s_and_saveexec_b64 s[2:3], vcc
	s_cbranch_execz .LBB0_1213
	global_load_dword v222, v[8:9], off
.LBB0_1213:
	s_or_b64 exec, exec, s[2:3]
	s_and_saveexec_b64 s[2:3], vcc
	s_cbranch_execz .LBB0_1215
	global_load_dword v223, v[8:9], off offset:4
.LBB0_1215:
	s_or_b64 exec, exec, s[2:3]
	v_or_b32_e32 v8, v13, v11
	v_lshlrev_b32_e32 v162, 2, v8
	v_lshl_add_u64 v[8:9], v[74:75], 0, v[162:163]
	v_mov_b32_e32 v54, 0
	v_mov_b32_e32 v58, 0
	s_and_saveexec_b64 s[2:3], vcc
	s_cbranch_execz .LBB0_1217
	global_load_dword v224, v[8:9], off
.LBB0_1217:
	s_or_b64 exec, exec, s[2:3]
	s_and_saveexec_b64 s[2:3], vcc
	s_cbranch_execz .LBB0_1219
	global_load_dword v225, v[8:9], off offset:4
.LBB0_1219:
	s_or_b64 exec, exec, s[2:3]
	v_or_b32_e32 v8, v14, v11
	v_lshlrev_b32_e32 v162, 2, v8
	v_lshl_add_u64 v[8:9], v[74:75], 0, v[162:163]
	v_mov_b32_e32 v55, 0
	v_mov_b32_e32 v59, 0
	s_and_saveexec_b64 s[2:3], vcc
	s_cbranch_execz .LBB0_1221
	global_load_dword v226, v[8:9], off
.LBB0_1221:
	s_or_b64 exec, exec, s[2:3]
	s_and_saveexec_b64 s[2:3], vcc
	s_cbranch_execz .LBB0_1223
	global_load_dword v227, v[8:9], off offset:4
.LBB0_1223:
	s_or_b64 exec, exec, s[2:3]
	v_or_b32_e32 v8, v15, v11
	v_lshlrev_b32_e32 v162, 2, v8
	v_lshl_add_u64 v[8:9], v[74:75], 0, v[162:163]
	v_mov_b32_e32 v61, 0
	v_mov_b32_e32 v60, 0
	s_and_saveexec_b64 s[2:3], vcc
	s_cbranch_execz .LBB0_1225
	global_load_dword v228, v[8:9], off
.LBB0_1225:
	s_or_b64 exec, exec, s[2:3]
	s_and_saveexec_b64 s[2:3], vcc
	s_cbranch_execz .LBB0_1227
	global_load_dword v229, v[8:9], off offset:4
.LBB0_1227:
	s_or_b64 exec, exec, s[2:3]
	v_or_b32_e32 v8, v16, v11
	v_lshlrev_b32_e32 v162, 2, v8
	v_lshl_add_u64 v[8:9], v[74:75], 0, v[162:163]
	v_mov_b32_e32 v63, 0
	v_mov_b32_e32 v62, 0
	s_and_saveexec_b64 s[2:3], vcc
	s_cbranch_execz .LBB0_1229
	global_load_dword v230, v[8:9], off
.LBB0_1229:
	s_or_b64 exec, exec, s[2:3]
	s_and_saveexec_b64 s[2:3], vcc
	s_cbranch_execz .LBB0_1231
	global_load_dword v231, v[8:9], off offset:4
.LBB0_1231:
	s_or_b64 exec, exec, s[2:3]
	v_or_b32_e32 v8, v17, v11
	v_lshlrev_b32_e32 v162, 2, v8
	v_lshl_add_u64 v[8:9], v[74:75], 0, v[162:163]
	v_mov_b32_e32 v85, 0
	v_mov_b32_e32 v84, 0
	s_and_saveexec_b64 s[2:3], vcc
	s_cbranch_execz .LBB0_1233
	global_load_dword v232, v[8:9], off
.LBB0_1233:
	s_or_b64 exec, exec, s[2:3]
	s_and_saveexec_b64 s[2:3], vcc
	s_cbranch_execz .LBB0_1235
	global_load_dword v233, v[8:9], off offset:4
.LBB0_1235:
	s_or_b64 exec, exec, s[2:3]
	v_or_b32_e32 v8, v18, v11
	v_lshlrev_b32_e32 v162, 2, v8
	v_lshl_add_u64 v[8:9], v[74:75], 0, v[162:163]
	v_mov_b32_e32 v87, 0
	v_mov_b32_e32 v86, 0
	s_and_saveexec_b64 s[2:3], vcc
	s_cbranch_execz .LBB0_1237
	global_load_dword v234, v[8:9], off
.LBB0_1237:
	s_or_b64 exec, exec, s[2:3]
	s_and_saveexec_b64 s[2:3], vcc
	s_cbranch_execz .LBB0_1239
	global_load_dword v235, v[8:9], off offset:4
.LBB0_1239:
	s_or_b64 exec, exec, s[2:3]
	s_waitcnt vmcnt(0)
	s_and_saveexec_b64 s[2:3], vcc
	v_cvt_pk_bf16_f32 v28, v164, s0
	v_cvt_pk_bf16_f32 v24, v165, s0
	v_cvt_pk_bf16_f32 v36, v166, s0
	v_cvt_pk_bf16_f32 v29, v167, s0
	v_cvt_pk_bf16_f32 v37, v170, s0
	v_cvt_pk_bf16_f32 v25, v171, s0
	v_cvt_pk_bf16_f32 v38, v172, s0
	v_cvt_pk_bf16_f32 v30, v173, s0
	v_cvt_pk_bf16_f32 v39, v174, s0
	v_cvt_pk_bf16_f32 v26, v175, s0
	v_cvt_pk_bf16_f32 v40, v176, s0
	v_cvt_pk_bf16_f32 v31, v177, s0
	v_cvt_pk_bf16_f32 v41, v178, s0
	v_cvt_pk_bf16_f32 v27, v179, s0
	v_cvt_pk_bf16_f32 v42, v180, s0
	v_cvt_pk_bf16_f32 v43, v181, s0
	v_cvt_pk_bf16_f32 v20, v182, s0
	v_cvt_pk_bf16_f32 v21, v183, s0
	v_cvt_pk_bf16_f32 v45, v184, s0
	v_cvt_pk_bf16_f32 v22, v185, s0
	v_cvt_pk_bf16_f32 v46, v186, s0
	v_cvt_pk_bf16_f32 v23, v187, s0
	v_cvt_pk_bf16_f32 v47, v190, s0
	v_cvt_pk_bf16_f32 v48, v191, s0
	v_cvt_pk_bf16_f32 v49, v192, s0
	v_cvt_pk_bf16_f32 v50, v193, s0
	v_cvt_pk_bf16_f32 v51, v198, s0
	v_cvt_pk_bf16_f32 v64, v199, s0
	v_cvt_pk_bf16_f32 v65, v200, s0
	v_cvt_pk_bf16_f32 v19, v201, s0
	v_cvt_pk_bf16_f32 v66, v202, s0
	v_cvt_pk_bf16_f32 v67, v203, s0
	v_cvt_pk_bf16_f32 v68, v204, s0
	v_cvt_pk_bf16_f32 v69, v205, s0
	v_cvt_pk_bf16_f32 v70, v206, s0
	v_cvt_pk_bf16_f32 v71, v207, s0
	v_cvt_pk_bf16_f32 v78, v208, s0
	v_cvt_pk_bf16_f32 v79, v209, s0
	v_cvt_pk_bf16_f32 v90, v210, s0
	v_cvt_pk_bf16_f32 v91, v211, s0
	v_cvt_pk_bf16_f32 v92, v212, s0
	v_cvt_pk_bf16_f32 v93, v213, s0
	v_cvt_pk_bf16_f32 v94, v214, s0
	v_cvt_pk_bf16_f32 v95, v215, s0
	v_cvt_pk_bf16_f32 v97, v216, s0
	v_cvt_pk_bf16_f32 v98, v217, s0
	v_cvt_pk_bf16_f32 v99, v218, s0
	v_cvt_pk_bf16_f32 v100, v219, s0
	v_cvt_pk_bf16_f32 v56, v220, s0
	v_cvt_pk_bf16_f32 v52, v221, s0
	v_cvt_pk_bf16_f32 v57, v222, s0
	v_cvt_pk_bf16_f32 v53, v223, s0
	v_cvt_pk_bf16_f32 v58, v224, s0
	v_cvt_pk_bf16_f32 v54, v225, s0
	v_cvt_pk_bf16_f32 v59, v226, s0
	v_cvt_pk_bf16_f32 v55, v227, s0
	v_cvt_pk_bf16_f32 v60, v228, s0
	v_cvt_pk_bf16_f32 v61, v229, s0
	v_cvt_pk_bf16_f32 v62, v230, s0
	v_cvt_pk_bf16_f32 v63, v231, s0
	v_cvt_pk_bf16_f32 v84, v232, s0
	v_cvt_pk_bf16_f32 v85, v233, s0
	v_cvt_pk_bf16_f32 v86, v234, s0
	v_cvt_pk_bf16_f32 v87, v235, s0
	s_or_b64 exec, exec, s[2:3]
	v_readlane_b32 s2, v255, 24
	s_mov_b32 s4, 0x5040100
	s_lshl_b32 s8, s2, 5
	v_perm_b32 v28, v36, v28, s4
	v_or_b32_e32 v36, s8, v89
	v_perm_b32 v24, v29, v24, s4
	v_perm_b32 v29, v38, v37, s4
	v_ashrrev_i32_e32 v37, 31, v36
	v_lshlrev_b64 v[36:37], 12, v[36:37]
	s_lshl_b32 s9, s2, 9
	v_lshl_or_b32 v36, v32, 8, v36
	v_or3_b32 v32, v33, s9, v32
	v_ashrrev_i32_e32 v33, 31, v32
	v_lshl_add_u64 v[32:33], v[32:33], 2, v[80:81]
	v_perm_b32 v9, v91, v79, s4
	global_load_dword v91, v[32:33], off
	v_ashrrev_i32_e32 v32, 5, v35
	s_mov_b32 s2, 0xfe03f81
	v_and_b32_e32 v34, 24, v34
	v_mul_hi_i32 v33, v32, s2
	v_lshlrev_b32_e32 v162, 2, v34
	v_lshrrev_b32_e32 v34, 31, v33
	v_ashrrev_i32_e32 v33, 4, v33
	v_add_u32_e32 v34, v33, v34
	v_mul_i32_i24_e32 v33, 0x102, v34
	v_perm_b32 v25, v30, v25, s4
	v_perm_b32 v30, v40, v39, s4
	v_lshl_add_u64 v[38:39], v[4:5], 0, v[36:37]
	v_lshl_add_u64 v[36:37], v[6:7], 0, v[36:37]
	v_sub_u32_e32 v32, v32, v33
	v_perm_b32 v27, v43, v27, s4
	v_perm_b32 v26, v31, v26, s4
	v_perm_b32 v31, v42, v41, s4
	v_lshl_add_u64 v[42:43], v[36:37], 0, v[162:163]
	v_ashrrev_i32_e32 v33, 31, v32
	v_mul_i32_i24_e32 v36, 0x4080, v34
	v_lshlrev_b64 v[32:33], 6, v[32:33]
	v_ashrrev_i32_e32 v37, 31, v36
	v_perm_b32 v18, v64, v50, s4
	v_perm_b32 v17, v48, v23, s4
	v_perm_b32 v16, v22, v21, s4
	v_perm_b32 v23, v66, v65, s4
	v_perm_b32 v22, v51, v49, s4
	v_perm_b32 v21, v47, v46, s4
	v_lshl_add_u64 v[64:65], v[38:39], 0, v[162:163]
	v_lshl_add_u64 v[40:41], v[32:33], 0, v[36:37]
	global_load_dwordx4 v[36:39], v[42:43], off offset:144
	global_load_dwordx4 v[46:49], v[42:43], off offset:128
	s_mov_b32 s2, 0x8000
	v_perm_b32 v10, v95, v93, s4
	v_perm_b32 v14, v94, v92, s4
	v_perm_b32 v20, v45, v20, s4
	v_perm_b32 v11, v100, v98, s4
	v_perm_b32 v15, v99, v97, s4
	v_perm_b32 v19, v67, v19, s4
	v_lshlrev_b32_e32 v35, 5, v35
	v_and_b32_e32 v162, 0x3e0, v35
	v_perm_b32 v8, v71, v69, s4
	v_perm_b32 v12, v70, v68, s4
	v_perm_b32 v13, v90, v78, s4
	v_perm_b32 v52, v53, v52, s4
	v_perm_b32 v53, v55, v54, s4
	v_perm_b32 v54, v63, v61, s4
	v_perm_b32 v55, v87, v85, s4
	s_waitcnt vmcnt(0)
	v_cvt_pk_bf16_f32 v32, v46, v47
	v_cvt_pk_bf16_f32 v33, v48, v49
	v_xor_b32_e32 v45, 0x8000, v33
	v_xor_b32_sdwa v92, s2, v33 dst_sel:DWORD dst_unused:UNUSED_PAD src0_sel:DWORD src1_sel:WORD_1
	v_xor_b32_e32 v93, 0x8000, v32
	v_xor_b32_sdwa v94, s2, v32 dst_sel:DWORD dst_unused:UNUSED_PAD src0_sel:DWORD src1_sel:WORD_1
	v_pk_add_f32 v[32:33], v[36:37], 0 neg_lo:[1,1] neg_hi:[1,1]
	v_perm_b32 v45, v92, v45, s4
	v_cvt_pk_bf16_f32 v46, v32, v33
	v_pk_add_f32 v[32:33], v[38:39], 0 neg_lo:[1,1] neg_hi:[1,1]
	global_load_dwordx4 v[36:39], v[42:43], off offset:16
	global_load_dwordx4 v[48:51], v[42:43], off
	v_cvt_pk_bf16_f32 v47, v32, v33
	s_waitcnt vmcnt(0)
	v_cvt_pk_bf16_f32 v32, v48, v49
	v_cvt_pk_bf16_f32 v33, v50, v51
	v_xor_b32_e32 v95, 0x8000, v33
	v_xor_b32_sdwa v97, s2, v33 dst_sel:DWORD dst_unused:UNUSED_PAD src0_sel:DWORD src1_sel:WORD_1
	v_xor_b32_e32 v98, 0x8000, v32
	v_xor_b32_sdwa v99, s2, v32 dst_sel:DWORD dst_unused:UNUSED_PAD src0_sel:DWORD src1_sel:WORD_1
	v_pk_add_f32 v[32:33], v[36:37], 0 neg_lo:[1,1] neg_hi:[1,1]
	s_nop 0
	v_cvt_pk_bf16_f32 v42, v32, v33
	v_pk_add_f32 v[32:33], v[38:39], 0 neg_lo:[1,1] neg_hi:[1,1]
	global_load_dwordx4 v[48:51], v[64:65], off offset:144
	global_load_dwordx4 v[36:39], v[64:65], off offset:128
	v_cvt_pk_bf16_f32 v43, v32, v33
	s_waitcnt vmcnt(0)
	v_cvt_pk_bf16_f32 v36, v36, v37
	v_cvt_pk_bf16_f32 v37, v38, v39
	v_cvt_pk_bf16_f32 v38, v48, v49
	v_cvt_pk_bf16_f32 v39, v50, v51
	global_load_dwordx4 v[48:51], v[64:65], off offset:16
	s_nop 0
	global_load_dwordx4 v[64:67], v[64:65], off
	s_waitcnt vmcnt(1)
	v_cvt_pk_bf16_f32 v34, v48, v49
	v_mov_b32_e32 v48, v160
	s_waitcnt vmcnt(0)
	v_cvt_pk_bf16_f32 v32, v64, v65
	v_and_or_b32 v40, v48, 63, v40
	v_mad_u64_u32 v[48:49], s[2:3], v40, s97, v[82:83]
	v_mad_i32_i24 v49, v41, s97, v49
	v_lshl_add_u64 v[40:41], v[48:49], 0, v[162:163]
	v_cvt_pk_bf16_f32 v33, v66, v67
	global_load_dwordx4 v[64:67], v[40:41], off offset:3600
	global_load_dwordx4 v[68:71], v[40:41], off offset:3584
	s_movk_i32 s2, 0x3300
	v_mul_lo_u32 v40, v44, s2
	s_mov_b64 s[2:3], 0x1ecc6000
	v_cvt_pk_bf16_f32 v35, v50, v51
	v_add_u32_e32 v90, 0x100, v40
	v_lshl_add_u64 v[78:79], v[2:3], 0, s[2:3]
	v_perm_b32 v44, v94, v93, s4
	v_perm_b32 v40, v99, v98, s4
	v_perm_b32 v41, v97, v95, s4
	v_perm_b32 v48, v57, v56, s4
	v_perm_b32 v49, v59, v58, s4
	v_perm_b32 v50, v62, v60, s4
	v_perm_b32 v51, v86, v84, s4
